# ssd_conv XBCP loads nt (no cache allocation on a miss; 3 percent halo reuse)
# speedup vs baseline: 1.0085x; 1.0033x over previous
;     __device__ __forceinline__ const char* a(const pg8::Unit& u) const { return (const char*)ws + aoff + (size_t)u.pm * 256 * K_ * 2 + (u.kq < 0 ? 0 : u.kq * (K_ / 4) * 2); }
;     __device__ __forceinline__ const char* b(const pg8::Unit& u) const { return (const char*)ws + boff + (size_t)u.pn * 256 * K_ * 2 + (u.kq < 0 ? 0 : u.kq * (K_ / 4) * 2); }
;     __device__ __forceinline__ const char* a(const pg8::Unit& u) const { return (const char*)ws + WS_A + (size_t)u.pm * 256 * D * 2; }
;     __device__ __forceinline__ const char* b(const pg8::Unit& u) const { return (const char*)ws + boff + (size_t)u.pn * 256 * D * 2; }
;     __device__ __forceinline__ const char* a(const pg8::Unit& u) const { return (const char*)ws + WS_A + (size_t)u.pm * 256 * D * 2; }
;     __device__ __forceinline__ const char* b(const pg8::Unit& u) const { return (const char*)ws + boff + (size_t)u.pn * 256 * D * 2; }
;     __device__ __forceinline__ const char* a(const pg8::Unit& u) const { return (const char*)ws + WS_W1 + (size_t)(u.pm & 1) * 256 * 256 * 2; }
;     __device__ __forceinline__ const char* b(const pg8::Unit& u) const { return (const char*)ws + WS_A + ((size_t)u.pn * 256 * D + (size_t)(u.pm >> 1) * 256) * 2; }
; __device__ __forceinline__ void ssd_conv_phase(Frame& F, int j, bool skip_ctx_c) {
;     ...
;         float w0[8], w1[8], w2[8], bi[8];
;         { const f32x4* p = (const f32x4*)(cw + c0); const f32x4 a = p[0], b = p[1]; w0[0] = a.x; w0[1] = a.y; w0[2] = a.z; w0[3] = a.w; w0[4] = b.x; w0[5] = b.y; w0[6] = b.z; w0[7] = b.w; }
;         { const f32x4* p = (const f32x4*)(cw + XBC + c0); const f32x4 a = p[0], b = p[1]; w1[0] = a.x; w1[1] = a.y; w1[2] = a.z; w1[3] = a.w; w1[4] = b.x; w1[5] = b.y; w1[6] = b.z; w1[7] = b.w; }
;         { const f32x4* p = (const f32x4*)(cw + 2 * XBC + c0); const f32x4 a = p[0], b = p[1]; w2[0] = a.x; w2[1] = a.y; w2[2] = a.z; w2[3] = a.w; w2[4] = b.x; w2[5] = b.y; w2[6] = b.z; w2[7] = b.w; }
;         { const f32x4* p = (const f32x4*)(cb_ + c0); const f32x4 a = p[0], b = p[1]; bi[0] = a.x; bi[1] = a.y; bi[2] = a.z; bi[3] = a.w; bi[4] = b.x; bi[5] = b.y; bi[6] = b.z; bi[7] = b.w; }
;         u32x4 raw[10];
; #pragma unroll
;         for (int i = 0; i < 10; ++i) { const int tt = tl - 1 + i; raw[i] = (tt >= 0 && tt < T) ? *(const u32x4*)(pre + (size_t)(seq0 + tt) * XBC + c0) : (u32x4){0u, 0u, 0u, 0u}; }
.LBB0_386:
	s_lshl_b32 s100, s7, 6
	s_lshl_b32 s101, s15, 6
	v_subrev_u32_e32 v72, s100, v93
	v_add_u32_e32 v72, s101, v72
	v_ashrrev_i32_e32 v73, 31, v72
	v_lshlrev_b64 v[12:13], 2, v[72:73]
	v_lshl_add_u64 v[4:5], s[0:1], 0, v[12:13]
	v_lshl_add_u64 v[8:9], s[30:31], 0, v[12:13]
	v_lshl_add_u64 v[14:15], s[34:35], 0, v[12:13]
	v_lshl_add_u64 v[16:17], s[10:11], 0, v[12:13]
	global_load_dwordx4 v[0:3], v[4:5], off offset:16
	global_load_dwordx4 v[56:59], v[4:5], off
	s_nop 0
	global_load_dwordx4 v[4:7], v[8:9], off offset:16
	global_load_dwordx4 v[52:55], v[8:9], off
	s_nop 0
	global_load_dwordx4 v[8:11], v[14:15], off offset:16
	global_load_dwordx4 v[48:51], v[14:15], off
	s_nop 0
	global_load_dwordx4 v[12:15], v[16:17], off offset:16
	global_load_dwordx4 v[60:63], v[16:17], off
	s_sub_i32 s4, s39, s26
	v_add_u32_e32 v74, s4, v92
	v_readlane_b32 s4, v252, 62
	v_add_u32_e32 v17, -1, v74
	v_readlane_b32 s5, v252, 63
	v_cmp_gt_u32_e32 vcc, s14, v17
	v_mov_b32_e32 v16, 0
	v_lshl_add_u64 v[78:79], v[72:73], 1, s[4:5]
	v_mov_b32_e32 v20, 0
	v_mov_b32_e32 v21, 0
	v_mov_b32_e32 v22, 0
	v_mov_b32_e32 v23, 0
	s_and_saveexec_b64 s[4:5], vcc
	s_cbranch_execz .LBB0_388
	v_add_u32_e32 v17, s26, v17
	s_movk_i32 s40, 0x3000
	v_mad_i64_i32 v[18:19], s[40:41], v17, s40, v[78:79]
	global_load_dwordx4 v[20:23], v[18:19], off nt
.LBB0_388:
	s_or_b64 exec, exec, s[4:5]
	v_cmp_gt_u32_e32 vcc, s14, v74
	v_add_u32_e32 v76, s39, v92
	v_mov_b32_e32 v17, 0
	v_mov_b32_e32 v18, 0
	v_mov_b32_e32 v19, 0
	s_and_saveexec_b64 s[4:5], vcc
	s_cbranch_execz .LBB0_390
	s_movk_i32 s39, 0x3000
	v_mad_i64_i32 v[16:17], s[40:41], v76, s39, v[78:79]
	global_load_dwordx4 v[16:19], v[16:17], off nt
.LBB0_390:
	s_or_b64 exec, exec, s[4:5]
	v_add_u32_e32 v29, 1, v74
	v_cmp_gt_u32_e32 vcc, s14, v29
	v_mov_b32_e32 v28, 0
	v_mov_b32_e32 v24, 0
	v_mov_b32_e32 v25, 0
	v_mov_b32_e32 v26, 0
	v_mov_b32_e32 v27, 0
	s_and_saveexec_b64 s[4:5], vcc
	s_cbranch_execz .LBB0_392
	v_add_u32_e32 v24, s26, v29
	s_movk_i32 s39, 0x3000
	v_mad_i64_i32 v[24:25], s[40:41], v24, s39, v[78:79]
	global_load_dwordx4 v[24:27], v[24:25], off nt
.LBB0_392:
	s_or_b64 exec, exec, s[4:5]
	v_add_u32_e32 v32, 2, v74
	v_cmp_gt_u32_e32 vcc, s14, v32
	v_mov_b32_e32 v29, 0
	v_mov_b32_e32 v30, 0
	v_mov_b32_e32 v31, 0
	s_and_saveexec_b64 s[4:5], vcc
	s_cbranch_execz .LBB0_394
	v_add_u32_e32 v28, s26, v32
	s_movk_i32 s39, 0x3000
	v_mad_i64_i32 v[28:29], s[40:41], v28, s39, v[78:79]
	global_load_dwordx4 v[28:31], v[28:29], off nt
.LBB0_394:
	s_or_b64 exec, exec, s[4:5]
	v_add_u32_e32 v37, 3, v74
	v_cmp_gt_u32_e32 vcc, s14, v37
	v_mov_b32_e32 v36, 0
	v_mov_b32_e32 v32, 0
	v_mov_b32_e32 v33, 0
	v_mov_b32_e32 v34, 0
	v_mov_b32_e32 v35, 0
	s_and_saveexec_b64 s[4:5], vcc
	s_cbranch_execz .LBB0_396
	v_add_u32_e32 v32, s26, v37
	s_movk_i32 s39, 0x3000
	v_mad_i64_i32 v[32:33], s[40:41], v32, s39, v[78:79]
	global_load_dwordx4 v[32:35], v[32:33], off nt
.LBB0_396:
	s_or_b64 exec, exec, s[4:5]
	v_add_u32_e32 v40, 4, v74
	v_cmp_gt_u32_e32 vcc, s14, v40
	v_mov_b32_e32 v37, 0
	v_mov_b32_e32 v38, 0
	v_mov_b32_e32 v39, 0
	s_and_saveexec_b64 s[4:5], vcc
	s_cbranch_execz .LBB0_398
	v_add_u32_e32 v36, s26, v40
	s_movk_i32 s39, 0x3000
	v_mad_i64_i32 v[36:37], s[40:41], v36, s39, v[78:79]
	global_load_dwordx4 v[36:39], v[36:37], off nt
.LBB0_398:
	s_or_b64 exec, exec, s[4:5]
	v_add_u32_e32 v45, 5, v74
	v_cmp_gt_u32_e32 vcc, s14, v45
	v_mov_b32_e32 v44, 0
	v_mov_b32_e32 v40, 0
	v_mov_b32_e32 v41, 0
	v_mov_b32_e32 v42, 0
	v_mov_b32_e32 v43, 0
	s_and_saveexec_b64 s[4:5], vcc
	s_cbranch_execz .LBB0_400
	v_add_u32_e32 v40, s26, v45
	s_movk_i32 s39, 0x3000
	v_mad_i64_i32 v[40:41], s[40:41], v40, s39, v[78:79]
	global_load_dwordx4 v[40:43], v[40:41], off nt
.LBB0_400:
	s_or_b64 exec, exec, s[4:5]
	v_add_u32_e32 v64, 6, v74
	v_cmp_gt_u32_e32 vcc, s14, v64
	v_mov_b32_e32 v45, 0
	v_mov_b32_e32 v46, 0
	v_mov_b32_e32 v47, 0
	s_and_saveexec_b64 s[4:5], vcc
	s_cbranch_execz .LBB0_402
	v_add_u32_e32 v44, s26, v64
	s_movk_i32 s39, 0x3000
	v_mad_i64_i32 v[44:45], s[40:41], v44, s39, v[78:79]
	global_load_dwordx4 v[44:47], v[44:45], off nt
.LBB0_402:
	s_or_b64 exec, exec, s[4:5]
	v_add_u32_e32 v65, 7, v74
	v_cmp_gt_u32_e32 vcc, s14, v65
	v_mov_b32_e32 v64, 0
	v_mov_b32_e32 v68, 0
	v_mov_b32_e32 v69, 0
	v_mov_b32_e32 v70, 0
	v_mov_b32_e32 v71, 0
	s_and_saveexec_b64 s[4:5], vcc
	s_cbranch_execz .LBB0_404
	v_add_u32_e32 v65, s26, v65
	s_movk_i32 s39, 0x3000
	v_mad_i64_i32 v[66:67], s[40:41], v65, s39, v[78:79]
	global_load_dwordx4 v[68:71], v[66:67], off nt
.LBB0_404:
	s_or_b64 exec, exec, s[4:5]
	v_add_u32_e32 v75, 8, v74
	v_cmp_gt_u32_e32 vcc, s14, v75
	v_mov_b32_e32 v65, 0
	v_mov_b32_e32 v66, 0
	v_mov_b32_e32 v67, 0
	s_and_saveexec_b64 s[4:5], vcc
	s_cbranch_execz .LBB0_406
	v_add_u32_e32 v64, s26, v75
	s_movk_i32 s26, 0x3000
	v_mad_i64_i32 v[64:65], s[40:41], v64, s26, v[78:79]
	global_load_dwordx4 v[64:67], v[64:65], off nt
